# FoX: s_setprio 1 over the MFMA half (it is the longer half now that the softmax half shrank)
# speedup vs baseline: 1.0009x; 1.0009x over previous
.Lfx_body:
	s_cmp_lt_u32 s62, 0x4000005e
	s_cselect_b64 s[78:79], -1, 0
	s_andn2_b64 vcc, exec, s[78:79]
	s_cbranch_vccnz .Lfx_h1_done
	s_andn2_b64 vcc, exec, s[80:81]
	s_cbranch_vccnz .Lfx_h1_qonly
	s_lshl_b32 s64, s41, 7
	s_mov_b32 s66, s64
	s_ashr_i32 s67, s64, 31
	s_lshl_b64 s[30:31], s[66:67], 8
	s_add_u32 s30, s23, s30
	s_addc_u32 s31, s24, s31
	s_add_i32 s66, s64, 0xffffff80
	s_ashr_i32 s67, s66, 31
	s_lshl_b64 s[28:29], s[66:67], 8
	s_add_u32 s28, s27, s28
	s_addc_u32 s29, s38, s29
	s_lshl_b64 s[68:69], s[66:67], 2
	s_add_u32 s68, s70, s68
	s_addc_u32 s69, s71, s69
	s_cmp_gt_u32 s63, 0
	s_cselect_b32 s82, 1, 0
	s_cmp_gt_i32 s41, 0
	s_cselect_b32 s84, s82, 0
	s_cmp_eq_u32 s40, 0
	s_cselect_b32 s86, s84, 0
	s_setprio 1
	s_add_i32 s64, s77, s51
	v_add_u32_e32 v10, s64, v183
	v_add_u32_e32 v11, s64, v184
	v_add_u32_e32 v12, s64, v185
	v_add_u32_e32 v13, s64, v186
	s_add_i32 s65, s76, s51
	v_add_u32_e32 v14, s65, v174
	s_lshl_b32 s66, s50, 2
	s_add_i32 s66, s66, s76
	v_lshl_add_u32 v0, v144, 2, s66
	v_add_u32_e32 v0, 0x10000, v0
	s_waitcnt lgkmcnt(6)
	v_mfma_f32_32x32x16_bf16 v[64:79], v[2:5], v[196:199], v[64:79]
	ds_read_b64_tr_b16 v[220:221], v11 offset:32768
	ds_read_b64_tr_b16 v[222:223], v11 offset:34816
	ds_read_b128 v[96:99], v0
	s_waitcnt lgkmcnt(7)
	v_mfma_f32_32x32x16_bf16 v[64:79], v[6:9], v[204:207], v[64:79]
	ds_read_b64_tr_b16 v[224:225], v11 offset:36864
	ds_read_b64_tr_b16 v[226:227], v11 offset:38912
	s_cmp_eq_u32 s84, 0
	s_cbranch_scc1 .Lfx_dm1_pq
	s_add_i32 s33, s73, s77
	s_mov_b32 m0, s33
	s_nop 0
	global_load_lds_dwordx4 v163, s[28:29]

.Lfx_hw1_pq:
	s_barrier
	v_mfma_f32_32x32x16_bf16 v[96:111], v[220:223], v[136:139], v[96:111]
	v_mfma_f32_32x32x16_bf16 v[80:95], v[224:227], v[136:139], v[80:95]
	v_mfma_f32_32x32x16_bf16 v[96:111], v[228:231], v[140:143], v[96:111]
	v_mfma_f32_32x32x16_bf16 v[80:95], v[232:235], v[140:143], v[80:95]
	s_setprio 0
	s_nop 7
	s_branch .Lfx_h1_joined
.Lfx_h1_qonly:
	s_lshl_b32 s64, s41, 7
	s_mov_b32 s66, s64
	s_ashr_i32 s67, s64, 31
	s_lshl_b64 s[30:31], s[66:67], 8
	s_add_u32 s30, s23, s30
	s_addc_u32 s31, s24, s31
	s_add_i32 s66, s64, 0xffffff80
	s_ashr_i32 s67, s66, 31
	s_lshl_b64 s[28:29], s[66:67], 8
	s_add_u32 s28, s27, s28
	s_addc_u32 s29, s38, s29
	s_lshl_b64 s[68:69], s[66:67], 2
	s_add_u32 s68, s70, s68
	s_addc_u32 s69, s71, s69
	s_cmp_gt_u32 s63, 0
	s_cselect_b32 s82, 1, 0
	s_cmp_gt_i32 s41, 0
	s_cselect_b32 s84, s82, 0
	s_cmp_eq_u32 s40, 0
	s_cselect_b32 s86, s84, 0
	s_setprio 1
	s_add_i32 s65, s76, s51
	v_add_u32_e32 v14, s65, v174
	s_lshl_b32 s66, s50, 2
	s_add_i32 s66, s66, s76
	v_lshl_add_u32 v0, v144, 2, s66
	v_add_u32_e32 v0, 0x10000, v0
	ds_read_b128 v[96:99], v0
	ds_read_b128 v[100:103], v0 offset:32
	ds_read_b128 v[80:83], v0 offset:128
	ds_read_b128 v[84:87], v0 offset:160
	ds_read_b128 v[104:107], v0 offset:64
	ds_read_b128 v[108:111], v0 offset:96
	ds_read_b128 v[88:91], v0 offset:192
	ds_read_b128 v[92:95], v0 offset:224
	v_add_u32_e32 v15, v14, v175
	ds_read_b128 v[2:5], v15
	ds_read_b128 v[6:9], v15 offset:8192
	v_add_u32_e32 v15, v14, v176
	ds_read_b128 v[212:215], v15
	ds_read_b128 v[216:219], v15 offset:8192
	s_waitcnt lgkmcnt(3)
	v_mfma_f32_32x32x16_bf16 v[96:111], v[2:5], v[112:115], v[96:111]
	v_add_u32_e32 v15, v14, v177
	ds_read_b128 v[220:223], v15
	s_waitcnt lgkmcnt(3)
	v_mfma_f32_32x32x16_bf16 v[80:95], v[6:9], v[112:115], v[80:95]
	ds_read_b128 v[224:227], v15 offset:8192
	s_cmp_eq_u32 s84, 0
	s_cbranch_scc1 .Lfx_dm6_q
	s_add_i32 s33, s73, s77
	s_mov_b32 m0, s33
	s_nop 0
	global_load_lds_dwordx4 v163, s[28:29]

.Lfx_hw1_q:
	s_barrier
	v_mfma_f32_32x32x16_bf16 v[96:111], v[220:223], v[136:139], v[96:111]
	v_mfma_f32_32x32x16_bf16 v[80:95], v[224:227], v[136:139], v[80:95]
	v_mfma_f32_32x32x16_bf16 v[96:111], v[228:231], v[140:143], v[96:111]
	v_mfma_f32_32x32x16_bf16 v[80:95], v[232:235], v[140:143], v[80:95]
	s_setprio 0
	s_add_i32 s29, s62, 0xc0000001
	s_cmp_gt_u32 s29, 0xc000005d
	s_cbranch_scc1 .Lfx_nomask_q
	s_nop 11
	v_add_u32_e32 v0, s62, v147
	v_subrev_u32_e32 v2, 30, v0
	v_cmp_gt_u32_e32 vcc, 2.0, v2
	v_add_u32_e32 v2, 0xbfffffc2, v0
	s_nop 3
	v_cndmask_b32_e32 v96, v187, v96, vcc
	v_cmp_lt_u32_e32 vcc, s17, v2
	v_subrev_u32_e32 v2, 31, v0
	s_nop 0
	v_cndmask_b32_e32 v80, v187, v80, vcc
	v_cmp_gt_u32_e32 vcc, 2.0, v2
	v_add_u32_e32 v2, 0xbfffffc1, v0
	s_nop 0
	v_cndmask_b32_e32 v97, v187, v97, vcc
	v_cmp_lt_u32_e32 vcc, s17, v2
	v_subrev_u32_e32 v2, 32, v0
	s_nop 0
	v_cndmask_b32_e32 v81, v187, v81, vcc
	v_cmp_gt_u32_e32 vcc, 2.0, v2
	v_add_u32_e32 v2, 0xbfffffc0, v0
	s_nop 0
	v_cndmask_b32_e32 v98, v187, v98, vcc
	v_cmp_lt_u32_e32 vcc, s17, v2
	v_subrev_u32_e32 v2, 33, v0
	s_nop 0
	v_cndmask_b32_e32 v82, v187, v82, vcc
	v_cmp_gt_u32_e32 vcc, 2.0, v2
	v_add_u32_e32 v2, 0xbfffffbf, v0
	s_nop 0
	v_cndmask_b32_e32 v99, v187, v99, vcc
	v_cmp_lt_u32_e32 vcc, s17, v2
	v_subrev_u32_e32 v2, 38, v0
	s_nop 0
	v_cndmask_b32_e32 v83, v187, v83, vcc
	v_cmp_gt_u32_e32 vcc, 2.0, v2
	v_add_u32_e32 v2, 0xbfffffba, v0
	s_nop 0
	v_cndmask_b32_e32 v100, v187, v100, vcc
	v_cmp_lt_u32_e32 vcc, s17, v2
	v_subrev_u32_e32 v2, 39, v0
	s_nop 0
	v_cndmask_b32_e32 v84, v187, v84, vcc
	v_cmp_gt_u32_e32 vcc, 2.0, v2
	v_add_u32_e32 v2, 0xbfffffb9, v0
	s_nop 0
	v_cndmask_b32_e32 v101, v187, v101, vcc
	v_cmp_lt_u32_e32 vcc, s17, v2
	v_subrev_u32_e32 v2, 40, v0
	s_nop 0
	v_cndmask_b32_e32 v85, v187, v85, vcc
	v_cmp_gt_u32_e32 vcc, 2.0, v2
	v_add_u32_e32 v2, 0xbfffffb8, v0
	s_nop 0
	v_cndmask_b32_e32 v102, v187, v102, vcc
	v_cmp_lt_u32_e32 vcc, s17, v2
	v_subrev_u32_e32 v2, 41, v0
	s_nop 0
	v_cndmask_b32_e32 v86, v187, v86, vcc
	v_cmp_gt_u32_e32 vcc, 2.0, v2
	v_add_u32_e32 v2, 0xbfffffb7, v0
	s_nop 0
	v_cndmask_b32_e32 v103, v187, v103, vcc
	v_cmp_lt_u32_e32 vcc, s17, v2
	v_subrev_u32_e32 v2, 46, v0
	s_nop 0
	v_cndmask_b32_e32 v87, v187, v87, vcc
	v_cmp_gt_u32_e32 vcc, 2.0, v2
	v_add_u32_e32 v2, 0xbfffffb2, v0
	s_nop 0
	v_cndmask_b32_e32 v104, v187, v104, vcc
	v_cmp_lt_u32_e32 vcc, s17, v2
	v_subrev_u32_e32 v2, 47, v0
	s_nop 0
	v_cndmask_b32_e32 v88, v187, v88, vcc
	v_cmp_gt_u32_e32 vcc, 2.0, v2
	v_add_u32_e32 v2, 0xbfffffb1, v0
	s_nop 0
	v_cndmask_b32_e32 v105, v187, v105, vcc
	v_cmp_lt_u32_e32 vcc, s17, v2
	v_subrev_u32_e32 v2, 48, v0
	s_nop 0
	v_cndmask_b32_e32 v89, v187, v89, vcc
	v_cmp_gt_u32_e32 vcc, 2.0, v2
	v_add_u32_e32 v2, 0xbfffffb0, v0
	s_nop 0
	v_cndmask_b32_e32 v106, v187, v106, vcc
	v_cmp_lt_u32_e32 vcc, s17, v2
	v_subrev_u32_e32 v2, 49, v0
	s_nop 0
	v_cndmask_b32_e32 v90, v187, v90, vcc
	v_cmp_gt_u32_e32 vcc, 2.0, v2
	v_add_u32_e32 v2, 0xbfffffaf, v0
	s_nop 0
	v_cndmask_b32_e32 v107, v187, v107, vcc
	v_cmp_lt_u32_e32 vcc, s17, v2
	v_subrev_u32_e32 v2, 54, v0
	s_nop 0
	v_cndmask_b32_e32 v91, v187, v91, vcc
	v_cmp_gt_u32_e32 vcc, 2.0, v2
	v_add_u32_e32 v2, 0xbfffffaa, v0
	s_nop 0
	v_cndmask_b32_e32 v108, v187, v108, vcc
	v_cmp_lt_u32_e32 vcc, s17, v2
	v_subrev_u32_e32 v2, 55, v0
	s_nop 0
	v_cndmask_b32_e32 v92, v187, v92, vcc
	v_cmp_gt_u32_e32 vcc, 2.0, v2
	v_add_u32_e32 v2, 0xbfffffa9, v0
	s_nop 0
	v_cndmask_b32_e32 v109, v187, v109, vcc
	v_cmp_lt_u32_e32 vcc, s17, v2
	v_subrev_u32_e32 v2, 56, v0
	s_nop 0
	v_cndmask_b32_e32 v93, v187, v93, vcc
	v_cmp_gt_u32_e32 vcc, 2.0, v2
	v_add_u32_e32 v2, 0xbfffffa8, v0
	s_nop 0
	v_cndmask_b32_e32 v110, v187, v110, vcc
	v_cmp_lt_u32_e32 vcc, s17, v2
	v_subrev_u32_e32 v2, 57, v0
	v_add_u32_e32 v0, 0xbfffffa7, v0
	v_cndmask_b32_e32 v94, v187, v94, vcc
	v_cmp_gt_u32_e32 vcc, 2.0, v2
	s_nop 1
	v_cndmask_b32_e32 v111, v187, v111, vcc
	v_cmp_lt_u32_e32 vcc, s17, v0
	s_nop 1
	v_cndmask_b32_e32 v95, v187, v95, vcc

.Lfx_w1_i:
.Lfx_h2_done:
	s_barrier
	s_add_i32 s63, s63, 1
	s_add_i32 s41, s41, -1
	s_addk_i32 s62, 0x80
	s_xor_b32 s76, s76, 0x10200
	s_xor_b32 s77, s77, 0x10200
	s_mov_b64 s[80:81], s[78:79]
	s_cmp_eq_u32 s41, -1
	s_cbranch_scc0 .Lfx_body
	s_andn2_b64 vcc, exec, s[80:81]
	s_cbranch_vccnz .Lfx_tail_done
	s_setprio 1
	s_add_i32 s64, s77, s51
	v_add_u32_e32 v10, s64, v183
	v_add_u32_e32 v11, s64, v184
	v_add_u32_e32 v12, s64, v185
	v_add_u32_e32 v13, s64, v186
	s_waitcnt lgkmcnt(6)
	v_mfma_f32_32x32x16_bf16 v[64:79], v[2:5], v[196:199], v[64:79]
	ds_read_b64_tr_b16 v[220:221], v11 offset:32768
	ds_read_b64_tr_b16 v[222:223], v11 offset:34816
	s_waitcnt lgkmcnt(6)
	v_mfma_f32_32x32x16_bf16 v[64:79], v[6:9], v[204:207], v[64:79]
	ds_read_b64_tr_b16 v[224:225], v11 offset:36864
	ds_read_b64_tr_b16 v[226:227], v11 offset:38912
	s_waitcnt lgkmcnt(6)
	v_mfma_f32_32x32x16_bf16 v[64:79], v[212:215], v[200:203], v[64:79]
	ds_read_b64_tr_b16 v[228:229], v11 offset:40960
	ds_read_b64_tr_b16 v[230:231], v11 offset:43008
	s_waitcnt lgkmcnt(6)
	v_mfma_f32_32x32x16_bf16 v[64:79], v[216:219], v[208:211], v[64:79]
	ds_read_b64_tr_b16 v[232:233], v11 offset:45056
	ds_read_b64_tr_b16 v[234:235], v11 offset:47104
	s_waitcnt lgkmcnt(6)
	v_mfma_f32_32x32x16_bf16 v[48:63], v[220:223], v[196:199], v[48:63]
	ds_read_b64_tr_b16 v[2:3], v12 offset:32768
	ds_read_b64_tr_b16 v[4:5], v12 offset:34816
	s_waitcnt lgkmcnt(6)
	v_mfma_f32_32x32x16_bf16 v[48:63], v[224:227], v[204:207], v[48:63]
	ds_read_b64_tr_b16 v[6:7], v12 offset:36864
	ds_read_b64_tr_b16 v[8:9], v12 offset:38912
	s_waitcnt lgkmcnt(6)
	v_mfma_f32_32x32x16_bf16 v[48:63], v[228:231], v[200:203], v[48:63]
	ds_read_b64_tr_b16 v[212:213], v12 offset:40960
	ds_read_b64_tr_b16 v[214:215], v12 offset:43008
	s_waitcnt lgkmcnt(6)
	v_mfma_f32_32x32x16_bf16 v[48:63], v[232:235], v[208:211], v[48:63]
	ds_read_b64_tr_b16 v[216:217], v12 offset:45056
	ds_read_b64_tr_b16 v[218:219], v12 offset:47104
	s_waitcnt lgkmcnt(6)
	v_mfma_f32_32x32x16_bf16 v[32:47], v[2:5], v[196:199], v[32:47]
	ds_read_b64_tr_b16 v[220:221], v13 offset:32768
	ds_read_b64_tr_b16 v[222:223], v13 offset:34816
	s_waitcnt lgkmcnt(6)
	v_mfma_f32_32x32x16_bf16 v[32:47], v[6:9], v[204:207], v[32:47]
	ds_read_b64_tr_b16 v[224:225], v13 offset:36864
	ds_read_b64_tr_b16 v[226:227], v13 offset:38912
	s_waitcnt lgkmcnt(6)
	v_mfma_f32_32x32x16_bf16 v[32:47], v[212:215], v[200:203], v[32:47]
	ds_read_b64_tr_b16 v[228:229], v13 offset:40960
	ds_read_b64_tr_b16 v[230:231], v13 offset:43008
	s_waitcnt lgkmcnt(6)
	v_mfma_f32_32x32x16_bf16 v[32:47], v[216:219], v[208:211], v[32:47]
	ds_read_b64_tr_b16 v[232:233], v13 offset:45056
	ds_read_b64_tr_b16 v[234:235], v13 offset:47104
	s_waitcnt lgkmcnt(6)
	v_mfma_f32_32x32x16_bf16 v[16:31], v[220:223], v[196:199], v[16:31]
	s_waitcnt lgkmcnt(4)
	v_mfma_f32_32x32x16_bf16 v[16:31], v[224:227], v[204:207], v[16:31]
	s_waitcnt lgkmcnt(2)
	v_mfma_f32_32x32x16_bf16 v[16:31], v[228:231], v[200:203], v[16:31]
	s_waitcnt lgkmcnt(0)
	v_mfma_f32_32x32x16_bf16 v[16:31], v[232:235], v[208:211], v[16:31]
	s_waitcnt vmcnt(0)
	s_setprio 0
